# attention: deferring waves fetch the first K/Q fragments of the step under their deferred PV MFMAs (on top of v104)
# speedup vs baseline: 1.0167x; 1.0030x over previous
.Lab_B:
	ds_read_b128 v[252:255], v199
	ds_read_b128 v[208:211], v193
	ds_read_b128 v[212:215], v199 offset:32
	s_cmp_eq_u32 s42, 0
	s_cbranch_scc1 .Lab_B0
	v_mfma_f32_32x32x16_bf16 v[128:143], v[216:219], v[200:203], v[128:143]
	v_mfma_f32_32x32x16_bf16 v[96:111], v[224:227], v[200:203], v[96:111]
	v_mfma_f32_32x32x16_bf16 v[64:79], v[232:235], v[200:203], v[64:79]
	v_mfma_f32_32x32x16_bf16 v[32:47], v[244:247], v[200:203], v[32:47]
	v_mfma_f32_32x32x16_bf16 v[128:143], v[220:223], v[204:207], v[128:143]
	v_mfma_f32_32x32x16_bf16 v[96:111], v[228:231], v[204:207], v[96:111]
	v_mfma_f32_32x32x16_bf16 v[64:79], v[236:239], v[204:207], v[64:79]
	v_mfma_f32_32x32x16_bf16 v[32:47], v[248:251], v[204:207], v[32:47]
.Lab_B0:
	ds_read_b128 v[236:239], v193 offset:32
	ds_read_b128 v[224:227], v199 offset:64
	ds_read_b128 v[244:247], v193 offset:64
	ds_read_b128 v[228:231], v199 offset:96
	ds_read_b128 v[248:251], v193 offset:96
	s_waitcnt lgkmcnt(6)
	v_mfma_f32_32x32x16_bf16 v[144:159], v[252:255], v[208:211], v[0:15]
	s_waitcnt lgkmcnt(4)
	v_mfma_f32_32x32x16_bf16 v[144:159], v[212:215], v[236:239], v[144:159]
	s_waitcnt lgkmcnt(2)
	v_mfma_f32_32x32x16_bf16 v[144:159], v[224:227], v[244:247], v[144:159]
	s_waitcnt lgkmcnt(0)
	v_mfma_f32_32x32x16_bf16 v[144:159], v[228:231], v[248:251], v[144:159]
	ds_read_b128 v[216:219], v199 offset:9216
	ds_read_b128 v[232:235], v193 offset:36864
	ds_read_b128 v[220:223], v199 offset:9248
	ds_read_b128 v[236:239], v193 offset:36896
	ds_read_b128 v[224:227], v199 offset:9280
	ds_read_b128 v[244:247], v193 offset:36928
	ds_read_b128 v[228:231], v199 offset:9312
	ds_read_b128 v[248:251], v193 offset:36960
	s_nop 3
	v_exp_f32_e32 v144, v144
	v_exp_f32_e32 v145, v145
	v_exp_f32_e32 v146, v146
	v_add_f32_e32 v243, v144, v145
	v_exp_f32_e32 v147, v147
	v_add_f32_e32 v243, v146, v243
	v_exp_f32_e32 v148, v148
	v_add_f32_e32 v243, v147, v243
	v_exp_f32_e32 v149, v149
	v_add_f32_e32 v243, v148, v243
	v_exp_f32_e32 v150, v150
	v_add_f32_e32 v243, v149, v243
	v_exp_f32_e32 v151, v151
	v_add_f32_e32 v243, v150, v243
	v_exp_f32_e32 v152, v152
	v_add_f32_e32 v243, v151, v243
	v_exp_f32_e32 v153, v153
	v_add_f32_e32 v243, v152, v243
	v_exp_f32_e32 v154, v154
	v_add_f32_e32 v243, v153, v243
	v_exp_f32_e32 v155, v155
	v_add_f32_e32 v243, v154, v243
	v_exp_f32_e32 v156, v156
	v_add_f32_e32 v243, v155, v243
	s_waitcnt lgkmcnt(6)
	v_mfma_f32_32x32x16_bf16 v[200:215], v[216:219], v[232:235], v[0:15]
	v_exp_f32_e32 v157, v157
	v_add_f32_e32 v243, v156, v243
	v_exp_f32_e32 v158, v158
	v_add_f32_e32 v243, v157, v243
	s_waitcnt lgkmcnt(4)
	v_mfma_f32_32x32x16_bf16 v[200:215], v[220:223], v[236:239], v[200:215]
	v_exp_f32_e32 v159, v159
	v_add_f32_e32 v243, v158, v243
	v_add_f32_e32 v243, v159, v243
	v_add_f32_e32 v196, v196, v243
	s_waitcnt lgkmcnt(2)
	v_mfma_f32_32x32x16_bf16 v[200:215], v[224:227], v[244:247], v[200:215]
	v_cvt_pk_bf16_f32 v144, v144, v145
	v_cvt_pk_bf16_f32 v145, v146, v147
	v_cvt_pk_bf16_f32 v146, v148, v149
	v_cvt_pk_bf16_f32 v147, v150, v151
	s_waitcnt lgkmcnt(0)
	v_mfma_f32_32x32x16_bf16 v[200:215], v[228:231], v[248:251], v[200:215]
	ds_read_b128 v[216:219], v198 offset:0
	ds_read_b128 v[224:227], v198 offset:4608
	ds_read_b128 v[232:235], v198 offset:9216
	ds_read_b128 v[244:247], v198 offset:13824
	ds_read_b128 v[220:223], v198 offset:32
	ds_read_b128 v[228:231], v198 offset:4640
	ds_read_b128 v[236:239], v198 offset:9248
	ds_read_b128 v[248:251], v198 offset:13856
	v_cvt_pk_bf16_f32 v148, v152, v153
	v_cvt_pk_bf16_f32 v149, v154, v155
	v_cvt_pk_bf16_f32 v150, v156, v157
	v_cvt_pk_bf16_f32 v151, v158, v159
	s_waitcnt lgkmcnt(7)
	v_mfma_f32_32x32x16_bf16 v[112:127], v[216:219], v[144:147], v[112:127]
	v_exp_f32_e32 v200, v200
	v_exp_f32_e32 v201, v201
	v_exp_f32_e32 v202, v202
	v_add_f32_e32 v243, v200, v201
	v_exp_f32_e32 v203, v203
	s_waitcnt lgkmcnt(6)
	v_mfma_f32_32x32x16_bf16 v[80:95], v[224:227], v[144:147], v[80:95]
	v_add_f32_e32 v243, v202, v243
	v_exp_f32_e32 v204, v204
	v_add_f32_e32 v243, v203, v243
	v_exp_f32_e32 v205, v205
	v_add_f32_e32 v243, v204, v243
	s_waitcnt lgkmcnt(5)
	v_mfma_f32_32x32x16_bf16 v[48:63], v[232:235], v[144:147], v[48:63]
	v_exp_f32_e32 v206, v206
	v_add_f32_e32 v243, v205, v243
	v_exp_f32_e32 v207, v207
	v_add_f32_e32 v243, v206, v243
	v_exp_f32_e32 v208, v208
	s_waitcnt lgkmcnt(4)
	v_mfma_f32_32x32x16_bf16 v[16:31], v[244:247], v[144:147], v[16:31]
	v_add_f32_e32 v243, v207, v243
	v_exp_f32_e32 v209, v209
	v_add_f32_e32 v243, v208, v243
	v_exp_f32_e32 v210, v210
	v_add_f32_e32 v243, v209, v243
	s_waitcnt lgkmcnt(3)
	v_mfma_f32_32x32x16_bf16 v[112:127], v[220:223], v[148:151], v[112:127]
	v_exp_f32_e32 v211, v211
	v_add_f32_e32 v243, v210, v243
	v_exp_f32_e32 v212, v212
	v_add_f32_e32 v243, v211, v243
	v_exp_f32_e32 v213, v213
	s_waitcnt lgkmcnt(2)
	v_mfma_f32_32x32x16_bf16 v[80:95], v[228:231], v[148:151], v[80:95]
	v_add_f32_e32 v243, v212, v243
	v_exp_f32_e32 v214, v214
	v_add_f32_e32 v243, v213, v243
	v_exp_f32_e32 v215, v215
	v_add_f32_e32 v243, v214, v243
	s_waitcnt lgkmcnt(1)
	v_mfma_f32_32x32x16_bf16 v[48:63], v[236:239], v[148:151], v[48:63]
	v_add_f32_e32 v243, v215, v243
	v_add_f32_e32 v197, v197, v243
	v_cvt_pk_bf16_f32 v200, v200, v201
	v_cvt_pk_bf16_f32 v201, v202, v203
	v_cvt_pk_bf16_f32 v202, v204, v205
	s_waitcnt lgkmcnt(0)
	v_mfma_f32_32x32x16_bf16 v[16:31], v[248:251], v[148:151], v[16:31]
	v_cvt_pk_bf16_f32 v203, v206, v207
	v_cvt_pk_bf16_f32 v204, v208, v209
	v_cvt_pk_bf16_f32 v205, v210, v211
	v_cvt_pk_bf16_f32 v206, v212, v213
	v_cvt_pk_bf16_f32 v207, v214, v215
	ds_read_b128 v[252:255], v199 offset:4608
	ds_read_b128 v[208:211], v193
	ds_read_b128 v[212:215], v199 offset:4640
	v_mfma_f32_32x32x16_bf16 v[128:143], v[216:219], v[200:203], v[128:143]
	v_mfma_f32_32x32x16_bf16 v[96:111], v[224:227], v[200:203], v[96:111]
	v_mfma_f32_32x32x16_bf16 v[64:79], v[232:235], v[200:203], v[64:79]
	v_mfma_f32_32x32x16_bf16 v[32:47], v[244:247], v[200:203], v[32:47]
	v_mfma_f32_32x32x16_bf16 v[128:143], v[220:223], v[204:207], v[128:143]
	v_mfma_f32_32x32x16_bf16 v[96:111], v[228:231], v[204:207], v[96:111]
	v_mfma_f32_32x32x16_bf16 v[64:79], v[236:239], v[204:207], v[64:79]
	v_mfma_f32_32x32x16_bf16 v[32:47], v[248:251], v[204:207], v[32:47]
	ds_read_b128 v[236:239], v193 offset:32
	ds_read_b128 v[224:227], v199 offset:4672
	ds_read_b128 v[244:247], v193 offset:64
	ds_read_b128 v[228:231], v199 offset:4704
	ds_read_b128 v[248:251], v193 offset:96
	s_waitcnt lgkmcnt(6)
	v_mfma_f32_32x32x16_bf16 v[144:159], v[252:255], v[208:211], v[0:15]
	s_waitcnt lgkmcnt(4)
	v_mfma_f32_32x32x16_bf16 v[144:159], v[212:215], v[236:239], v[144:159]
	s_waitcnt lgkmcnt(2)
	v_mfma_f32_32x32x16_bf16 v[144:159], v[224:227], v[244:247], v[144:159]
	s_waitcnt lgkmcnt(0)
	v_mfma_f32_32x32x16_bf16 v[144:159], v[228:231], v[248:251], v[144:159]
	ds_read_b128 v[216:219], v199 offset:13824
	ds_read_b128 v[232:235], v193 offset:36864
	ds_read_b128 v[220:223], v199 offset:13856
	ds_read_b128 v[236:239], v193 offset:36896
	ds_read_b128 v[224:227], v199 offset:13888
	ds_read_b128 v[244:247], v193 offset:36928
	ds_read_b128 v[228:231], v199 offset:13920
	ds_read_b128 v[248:251], v193 offset:36960
	s_nop 3
	v_exp_f32_e32 v144, v144
	v_exp_f32_e32 v145, v145
	v_exp_f32_e32 v146, v146
	v_add_f32_e32 v243, v144, v145
	v_exp_f32_e32 v147, v147
	v_add_f32_e32 v243, v146, v243
	v_exp_f32_e32 v148, v148
	v_add_f32_e32 v243, v147, v243
	v_exp_f32_e32 v149, v149
	v_add_f32_e32 v243, v148, v243
	v_exp_f32_e32 v150, v150
	v_add_f32_e32 v243, v149, v243
	v_exp_f32_e32 v151, v151
	v_add_f32_e32 v243, v150, v243
	v_exp_f32_e32 v152, v152
	v_add_f32_e32 v243, v151, v243
	v_exp_f32_e32 v153, v153
	v_add_f32_e32 v243, v152, v243
	v_exp_f32_e32 v154, v154
	v_add_f32_e32 v243, v153, v243
	v_exp_f32_e32 v155, v155
	v_add_f32_e32 v243, v154, v243
	v_exp_f32_e32 v156, v156
	v_add_f32_e32 v243, v155, v243
	s_waitcnt lgkmcnt(6)
	v_mfma_f32_32x32x16_bf16 v[200:215], v[216:219], v[232:235], v[0:15]
	v_exp_f32_e32 v157, v157
	v_add_f32_e32 v243, v156, v243
	v_exp_f32_e32 v158, v158
	v_add_f32_e32 v243, v157, v243
	s_waitcnt lgkmcnt(4)
	v_mfma_f32_32x32x16_bf16 v[200:215], v[220:223], v[236:239], v[200:215]
	v_exp_f32_e32 v159, v159
	v_add_f32_e32 v243, v158, v243
	v_add_f32_e32 v243, v159, v243
	v_add_f32_e32 v196, v196, v243
	s_waitcnt lgkmcnt(2)
	v_mfma_f32_32x32x16_bf16 v[200:215], v[224:227], v[244:247], v[200:215]
	v_cvt_pk_bf16_f32 v144, v144, v145
	v_cvt_pk_bf16_f32 v145, v146, v147
	v_cvt_pk_bf16_f32 v146, v148, v149
	v_cvt_pk_bf16_f32 v147, v150, v151
	s_waitcnt lgkmcnt(0)
	v_mfma_f32_32x32x16_bf16 v[200:215], v[228:231], v[248:251], v[200:215]
	ds_read_b128 v[216:219], v198 offset:64
	ds_read_b128 v[224:227], v198 offset:4672
	ds_read_b128 v[232:235], v198 offset:9280
	ds_read_b128 v[244:247], v198 offset:13888
	ds_read_b128 v[220:223], v198 offset:96
	ds_read_b128 v[228:231], v198 offset:4704
	ds_read_b128 v[236:239], v198 offset:9312
	ds_read_b128 v[248:251], v198 offset:13920
	v_cvt_pk_bf16_f32 v148, v152, v153
	v_cvt_pk_bf16_f32 v149, v154, v155
	v_cvt_pk_bf16_f32 v150, v156, v157
	v_cvt_pk_bf16_f32 v151, v158, v159
	s_waitcnt lgkmcnt(7)
	v_mfma_f32_32x32x16_bf16 v[112:127], v[216:219], v[144:147], v[112:127]
	v_exp_f32_e32 v200, v200
	v_exp_f32_e32 v201, v201
	v_exp_f32_e32 v202, v202
	v_add_f32_e32 v243, v200, v201
	v_exp_f32_e32 v203, v203
	s_waitcnt lgkmcnt(6)
	v_mfma_f32_32x32x16_bf16 v[80:95], v[224:227], v[144:147], v[80:95]
	v_add_f32_e32 v243, v202, v243
	v_exp_f32_e32 v204, v204
	v_add_f32_e32 v243, v203, v243
	v_exp_f32_e32 v205, v205
	v_add_f32_e32 v243, v204, v243
	s_waitcnt lgkmcnt(5)
	v_mfma_f32_32x32x16_bf16 v[48:63], v[232:235], v[144:147], v[48:63]
	v_exp_f32_e32 v206, v206
	v_add_f32_e32 v243, v205, v243
	v_exp_f32_e32 v207, v207
	v_add_f32_e32 v243, v206, v243
	v_exp_f32_e32 v208, v208
	s_waitcnt lgkmcnt(4)
	v_mfma_f32_32x32x16_bf16 v[16:31], v[244:247], v[144:147], v[16:31]
	v_add_f32_e32 v243, v207, v243
	v_exp_f32_e32 v209, v209
	v_add_f32_e32 v243, v208, v243
	v_exp_f32_e32 v210, v210
	v_add_f32_e32 v243, v209, v243
	s_waitcnt lgkmcnt(3)
	v_mfma_f32_32x32x16_bf16 v[112:127], v[220:223], v[148:151], v[112:127]
	v_exp_f32_e32 v211, v211
	v_add_f32_e32 v243, v210, v243
	v_exp_f32_e32 v212, v212
	v_add_f32_e32 v243, v211, v243
	v_exp_f32_e32 v213, v213
	s_waitcnt lgkmcnt(2)
	v_mfma_f32_32x32x16_bf16 v[80:95], v[228:231], v[148:151], v[80:95]
	v_add_f32_e32 v243, v212, v243
	v_exp_f32_e32 v214, v214
	v_add_f32_e32 v243, v213, v243
	v_exp_f32_e32 v215, v215
	v_add_f32_e32 v243, v214, v243
	s_waitcnt lgkmcnt(1)
	v_mfma_f32_32x32x16_bf16 v[48:63], v[236:239], v[148:151], v[48:63]
	v_add_f32_e32 v243, v215, v243
	v_add_f32_e32 v197, v197, v243
	v_cvt_pk_bf16_f32 v200, v200, v201
	v_cvt_pk_bf16_f32 v201, v202, v203
	v_cvt_pk_bf16_f32 v202, v204, v205
	s_waitcnt lgkmcnt(0)
	v_mfma_f32_32x32x16_bf16 v[16:31], v[248:251], v[148:151], v[16:31]
	v_cvt_pk_bf16_f32 v203, v206, v207
	v_cvt_pk_bf16_f32 v204, v208, v209
	v_cvt_pk_bf16_f32 v205, v210, v211
	v_cvt_pk_bf16_f32 v206, v212, v213
	v_cvt_pk_bf16_f32 v207, v214, v215
	s_add_i32 s6, s42, 1
	s_waitcnt vmcnt(0)
	s_cmp_eq_u32 s33, 0
	s_cbranch_scc0 .Lqt_s0_2
	v_add_u32_e32 v252, 0x9000, v190
	ds_write_b128 v189, v[160:163] offset:36864
	ds_write2_b64 v252, v[164:165], v[166:167] offset1:2
	ds_write_b128 v189, v[168:171] offset:46080
	v_add_u32_e32 v252, 0xb000, v190
	ds_write2_b64 v252, v[172:173], v[174:175] offset0:128 offset1:130
	s_branch .Lqt_pf_2
